# cooperative grid sync: pollers back off (s_sleep 12 between sc1 polls of the shared word) to reduce contention with the arrival atomics; stacked on stack35
# speedup vs baseline: 1.0006x; 1.0006x over previous
; #define SEAM(k) do { if (lo <= (k) && (k) + 1 < hi) grid.sync(); } while (0)
; __global__ void __launch_bounds__(NTHR, 2) mk_fwd(Args a) {
;     ...
;     SEAM(0);
.LBB0_49:
	s_sleep 12
	global_load_dword v2, v0, s[6:7] offset:32 sc1
	s_waitcnt vmcnt(0)
	v_and_b32_e32 v2, 0xffff0000, v2
	v_cmp_ne_u32_e32 vcc, v2, v1
	s_or_b64 s[8:9], vcc, s[8:9]
	s_andn2_b64 exec, exec, s[8:9]
	s_cbranch_execnz .LBB0_49
